# phase-5 router gate divisions (e/sum) as v_rcp_f32 + v_mul_f32 like the other epilogue divisions
# speedup vs baseline: 1.0124x; 1.0011x over previous
; DI unsigned pk2(float a, float b) { fl2_t f = {a, b}; bf2_t r = __builtin_convertvector(f, bf2_t); return __builtin_bit_cast(unsigned, r); }
; #define HSUM(v) do { v += __shfl_xor(v, 16, 64); v += __shfl_xor(v, 8, 64); v += __shfl_xor(v, 4, 64); v += __shfl_xor(v, 2, 64); v += __shfl_xor(v, 1, 64); } while (0)
; DI void phase5(const Params& p, char* lds0) {
;     ...
;     for (int i = 0; i < 8; ++i) {
;       const int tl = w * 16 + i * 2 + hw, t = chunk * 64 + tl;
;       int br, s, S; tok_info(t, br, s, S);
;       float hv[32];
;       float ss = 0.f;
; #pragma unroll
;       for (int j = 0; j < 8; ++j) {
;         float4 v = nx[j];
;         hv[j * 4 + 0] = v.x; hv[j * 4 + 1] = v.y; hv[j * 4 + 2] = v.z; hv[j * 4 + 3] = v.w;
;         ss += v.x * v.x + v.y * v.y + v.z * v.z + v.w * v.w;
;       }
;       if (i + 1 < 8) {
;         const float* x1 = p.out + (size_t)(t + 2) * D;
; #pragma unroll
;         for (int j = 0; j < 8; ++j) nx[j] = *(const float4*)(x1 + j * 128 + l32 * 4);
;       }
;     ...
;       HSUM(ss);
;       const float rstd = rsqrtf(ss * (1.f / 1024.f) + 1e-6f);
; #pragma unroll
;       for (int j = 0; j < 8; ++j) {
;         const int c = j * 128 + l32 * 4;
;         hv[j * 4 + 0] = hv[j * 4 + 0] * rstd * csv[j].x + shv[j].x;
;         hv[j * 4 + 1] = hv[j * 4 + 1] * rstd * csv[j].y + shv[j].y;
;         hv[j * 4 + 2] = hv[j * 4 + 2] * rstd * csv[j].z + shv[j].z;
;         hv[j * 4 + 3] = hv[j * 4 + 3] * rstd * csv[j].w + shv[j].w;
;         u32x2 o; o[0] = pk2(hv[j * 4 + 0], hv[j * 4 + 1]); o[1] = pk2(hv[j * 4 + 2], hv[j * 4 + 3]);
;         *(u32x2*)(H + (size_t)t * D + c) = o;
;       }
.LBB0_259:
	s_waitcnt vmcnt(16)
	v_pk_mul_f32 v[160:161], v[94:95], v[94:95]
	s_waitcnt vmcnt(15)
	v_pk_mul_f32 v[164:165], v[90:91], v[90:91]
	v_pk_mul_f32 v[162:163], v[96:97], v[96:97]
	v_pk_mul_f32 v[166:167], v[92:93], v[92:93]
	v_add_f32_e32 v159, v161, v160
	v_add_f32_e32 v160, v165, v164
	v_add_f32_e32 v159, v162, v159
	v_add_f32_e32 v160, v166, v160
	s_waitcnt vmcnt(14)
	v_pk_mul_f32 v[168:169], v[86:87], v[86:87]
	v_add_f32_e32 v159, v163, v159
	v_add_f32_e32 v160, v167, v160
	v_pk_mul_f32 v[170:171], v[88:89], v[88:89]
	v_add_f32_e32 v159, v160, v159
	v_add_f32_e32 v160, v169, v168
	v_add_f32_e32 v160, v170, v160
	s_waitcnt vmcnt(13)
	v_pk_mul_f32 v[172:173], v[78:79], v[78:79]
	v_add_f32_e32 v160, v171, v160
	v_pk_mul_f32 v[188:189], v[80:81], v[80:81]
	v_add_f32_e32 v159, v160, v159
	v_add_f32_e32 v160, v173, v172
	v_add_f32_e32 v160, v188, v160
	s_waitcnt vmcnt(12)
	v_pk_mul_f32 v[190:191], v[70:71], v[70:71]
	v_add_f32_e32 v160, v189, v160
	v_pk_mul_f32 v[192:193], v[72:73], v[72:73]
	v_add_f32_e32 v159, v160, v159
	v_add_f32_e32 v160, v191, v190
	v_add_f32_e32 v160, v192, v160
	s_waitcnt vmcnt(11)
	v_pk_mul_f32 v[194:195], v[82:83], v[82:83]
	v_add_f32_e32 v160, v193, v160
	v_pk_mul_f32 v[196:197], v[84:85], v[84:85]
	v_add_f32_e32 v159, v160, v159
	v_add_f32_e32 v160, v194, v195
	v_add_f32_e32 v160, v160, v196
	s_waitcnt vmcnt(10)
	v_pk_mul_f32 v[198:199], v[74:75], v[74:75]
	v_add_f32_e32 v160, v160, v197
	v_pk_mul_f32 v[200:201], v[76:77], v[76:77]
	v_add_f32_e32 v159, v160, v159
	v_add_f32_e32 v160, v198, v199
	v_add_f32_e32 v160, v160, v200
	s_waitcnt vmcnt(9)
	v_pk_mul_f32 v[202:203], v[66:67], v[66:67]
	v_add_f32_e32 v160, v160, v201
	v_pk_mul_f32 v[204:205], v[68:69], v[68:69]
	v_add_f32_e32 v159, v159, v160
	v_add_f32_e32 v160, v202, v203
	v_add_f32_e32 v160, v160, v204
	v_add_f32_e32 v160, v160, v205
	v_add_f32_e32 v159, v159, v160
	ds_bpermute_b32 v160, v176, v159
	s_waitcnt lgkmcnt(0)
	v_add_f32_e32 v159, v159, v160
	ds_bpermute_b32 v160, v177, v159
	s_waitcnt lgkmcnt(0)
	v_add_f32_e32 v159, v159, v160
	ds_bpermute_b32 v160, v178, v159
	s_waitcnt lgkmcnt(0)
	v_add_f32_e32 v159, v159, v160
	ds_bpermute_b32 v160, v179, v159
	s_waitcnt lgkmcnt(0)
	v_add_f32_e32 v159, v159, v160
	ds_bpermute_b32 v160, v180, v159
	s_waitcnt lgkmcnt(0)
	v_add_f32_e32 v159, v159, v160
	v_fmamk_f32 v159, v159, 0x3a800000, v182
	v_mul_f32_e32 v160, 0x4b800000, v159
	v_cmp_gt_f32_e32 vcc, s40, v159
	s_nop 1
	v_cndmask_b32_e32 v159, v159, v160, vcc
	v_rsq_f32_e32 v159, v159
	s_nop 0
	v_mul_f32_e32 v160, 0x45800000, v159
	v_cndmask_b32_e32 v168, v159, v160, vcc
	v_pk_mul_f32 v[94:95], v[94:95], v[168:169] op_sel_hi:[1,0]
	v_ashrrev_i32_e32 v159, 31, v158
	v_pk_fma_f32 v[160:161], v[126:127], v[94:95], v[2:3]
	v_pk_mul_f32 v[94:95], v[96:97], v[168:169] op_sel_hi:[1,0]
	v_lshlrev_b64 v[164:165], 11, v[158:159]
	v_pk_fma_f32 v[162:163], v[128:129], v[94:95], v[4:5]
	v_pk_mul_f32 v[90:91], v[90:91], v[168:169] op_sel_hi:[1,0]
	v_cvt_pk_bf16_f32 v94, v160, v161
	v_cvt_pk_bf16_f32 v95, v162, v163
	v_lshl_add_u64 v[166:167], v[110:111], 0, v[164:165]
	v_pk_fma_f32 v[164:165], v[130:131], v[90:91], v[6:7]
	v_pk_mul_f32 v[90:91], v[92:93], v[168:169] op_sel_hi:[1,0]
	global_store_dwordx2 v[166:167], v[94:95], off
	v_pk_fma_f32 v[94:95], v[132:133], v[90:91], v[8:9]
	v_cvt_pk_bf16_f32 v90, v164, v165
	v_cvt_pk_bf16_f32 v91, v94, v95
	v_pk_mul_f32 v[86:87], v[86:87], v[168:169] op_sel_hi:[1,0]
	global_store_dwordx2 v[166:167], v[90:91], off offset:256
	v_pk_fma_f32 v[90:91], v[134:135], v[86:87], v[10:11]
	v_pk_mul_f32 v[86:87], v[88:89], v[168:169] op_sel_hi:[1,0]
	v_pk_mul_f32 v[78:79], v[78:79], v[168:169] op_sel_hi:[1,0]
	v_pk_fma_f32 v[92:93], v[136:137], v[86:87], v[12:13]
	v_pk_mul_f32 v[70:71], v[70:71], v[168:169] op_sel_hi:[1,0]
	v_cvt_pk_bf16_f32 v86, v90, v91
	v_cvt_pk_bf16_f32 v87, v92, v93
	v_pk_fma_f32 v[96:97], v[138:139], v[78:79], v[14:15]
	v_pk_mul_f32 v[78:79], v[80:81], v[168:169] op_sel_hi:[1,0]
	v_pk_fma_f32 v[80:81], v[142:143], v[70:71], v[18:19]
	v_pk_mul_f32 v[70:71], v[72:73], v[168:169] op_sel_hi:[1,0]
	global_store_dwordx2 v[166:167], v[86:87], off offset:512
	v_pk_fma_f32 v[86:87], v[144:145], v[70:71], v[20:21]
	v_cvt_pk_bf16_f32 v70, v80, v81
	v_cvt_pk_bf16_f32 v71, v86, v87
	v_pk_fma_f32 v[88:89], v[140:141], v[78:79], v[16:17]
	global_store_dwordx2 v[166:167], v[70:71], off offset:1024
	v_pk_mul_f32 v[70:71], v[82:83], v[168:169] op_sel_hi:[1,0]
	v_cvt_pk_bf16_f32 v78, v96, v97
	v_cvt_pk_bf16_f32 v79, v88, v89
	v_pk_fma_f32 v[82:83], v[146:147], v[70:71], v[22:23]
	v_pk_mul_f32 v[70:71], v[84:85], v[168:169] op_sel_hi:[1,0]
	global_store_dwordx2 v[166:167], v[78:79], off offset:768
	v_pk_fma_f32 v[78:79], v[148:149], v[70:71], v[24:25]
	v_cvt_pk_bf16_f32 v70, v82, v83
	v_cvt_pk_bf16_f32 v71, v78, v79
	global_store_dwordx2 v[166:167], v[70:71], off offset:1280
	v_pk_mul_f32 v[70:71], v[74:75], v[168:169] op_sel_hi:[1,0]
	v_pk_mul_f32 v[72:73], v[76:77], v[168:169] op_sel_hi:[1,0]
	v_pk_fma_f32 v[70:71], v[150:151], v[70:71], v[26:27]
	v_pk_fma_f32 v[72:73], v[152:153], v[72:73], v[28:29]
	v_cvt_pk_bf16_f32 v74, v70, v71
	v_cvt_pk_bf16_f32 v75, v72, v73
	global_store_dwordx2 v[166:167], v[74:75], off offset:1536
	ds_read_b128 v[74:77], v102 offset:9216
	ds_read_b128 v[188:191], v102 offset:9728
	v_mov_b32_e32 v204, v91
	v_mov_b32_e32 v205, v97
	v_pk_mul_f32 v[170:171], v[66:67], v[168:169] op_sel_hi:[1,0]
	v_pk_mul_f32 v[66:67], v[68:69], v[168:169] op_sel_hi:[1,0]
	s_waitcnt lgkmcnt(0)
; #define HSUM(v) do { v += __shfl_xor(v, 16, 64); v += __shfl_xor(v, 8, 64); v += __shfl_xor(v, 4, 64); v += __shfl_xor(v, 2, 64); v += __shfl_xor(v, 1, 64); } while (0)
; DI void phase5(const Params& p, char* lds0) {
;     ...
;       float lg[4];
; #pragma unroll
;       for (int n = 0; n < 4; ++n) {
;         float a = 0.f;
; #pragma unroll
;         for (int j = 0; j < 8; ++j) {
;           float4 wv = *(const float4*)(wg + n * 1024 + j * 128 + l32 * 4);
;           a += hv[j * 4 + 0] * wv.x + hv[j * 4 + 1] * wv.y + hv[j * 4 + 2] * wv.z + hv[j * 4 + 3] * wv.w;
;         }
;         HSUM(a);
;         lg[n] = a + p.b_rg[n];
;       }
	v_mov_b32_e32 v85, v188
	v_mov_b32_e32 v188, v75
	v_mov_b32_e32 v84, v74
	v_mov_b32_e32 v68, v90
	v_mov_b32_e32 v69, v96
	v_pk_mul_f32 v[74:75], v[204:205], v[188:189]
	v_mov_b32_e32 v206, v92
	v_pk_fma_f32 v[74:75], v[68:69], v[84:85], v[74:75]
	v_mov_b32_e32 v84, v76
	v_mov_b32_e32 v85, v190
	v_mov_b32_e32 v207, v88
	v_pk_fma_f32 v[84:85], v[206:207], v[84:85], v[74:75]
	v_mov_b32_e32 v190, v77
	ds_read_b128 v[74:77], v102 offset:10240
	ds_read_b128 v[192:195], v102 offset:10752
	v_mov_b32_e32 v208, v93
	v_mov_b32_e32 v209, v89
	v_pk_fma_f32 v[168:169], v[208:209], v[190:191], v[84:85]
	v_mov_b32_e32 v212, v81
	s_waitcnt lgkmcnt(0)
	v_mov_b32_e32 v85, v192
	v_mov_b32_e32 v192, v75
	v_mov_b32_e32 v213, v83
	v_mov_b32_e32 v84, v74
	v_mov_b32_e32 v210, v80
	v_mov_b32_e32 v211, v82
	v_pk_mul_f32 v[74:75], v[212:213], v[192:193]
	v_mov_b32_e32 v188, v76
	v_pk_fma_f32 v[84:85], v[210:211], v[84:85], v[74:75]
	v_mov_b32_e32 v189, v194
	v_mov_b32_e32 v74, v86
	v_mov_b32_e32 v75, v78
	v_pk_fma_f32 v[84:85], v[74:75], v[188:189], v[84:85]
	ds_read_b128 v[188:191], v102 offset:8192
	ds_read_b128 v[196:199], v102 offset:12288
	v_mov_b32_e32 v194, v77
	v_mov_b32_e32 v76, v87
	v_mov_b32_e32 v77, v79
	v_pk_fma_f32 v[84:85], v[76:77], v[194:195], v[84:85]
	ds_read_b128 v[192:195], v102 offset:8704
	ds_read_b128 v[200:203], v102 offset:12800
	s_waitcnt lgkmcnt(2)
	v_pk_mov_b32 v[214:215], v[188:189], v[196:197] op_sel:[1,0]
	v_mov_b32_e32 v189, v197
	v_pk_mul_f32 v[188:189], v[188:189], v[160:161]
	v_mov_b32_e32 v196, v190
	v_pk_fma_f32 v[188:189], v[214:215], v[160:161], v[188:189] op_sel:[0,1,0] op_sel_hi:[1,0,1]
	v_mov_b32_e32 v197, v198
	v_pk_fma_f32 v[188:189], v[162:163], v[196:197], v[188:189] op_sel_hi:[0,1,1]
	v_mov_b32_e32 v198, v191
	v_pk_fma_f32 v[188:189], v[162:163], v[198:199], v[188:189] op_sel:[1,0,0]
	s_waitcnt vmcnt(7)
	v_pk_fma_f32 v[66:67], v[156:157], v[66:67], v[32:33]
	v_pk_add_f32 v[214:215], v[188:189], 0 op_sel_hi:[1,0]
	s_waitcnt lgkmcnt(0)
	v_pk_mov_b32 v[188:189], v[192:193], v[200:201] op_sel:[1,0]
	v_mov_b32_e32 v193, v201
	v_pk_mul_f32 v[190:191], v[164:165], v[192:193]
	v_cvt_pk_bf16_f32 v173, v66, v67
	v_pk_fma_f32 v[188:189], v[164:165], v[188:189], v[190:191] op_sel:[1,0,0] op_sel_hi:[0,1,1]
	v_mov_b32_e32 v190, v194
	v_mov_b32_e32 v191, v202
	v_pk_fma_f32 v[192:193], v[94:95], v[190:191], v[188:189] op_sel_hi:[0,1,1]
	ds_read_b128 v[188:191], v102 offset:13312
	ds_read_b128 v[196:199], v102 offset:13824
	v_mov_b32_e32 v202, v195
	v_pk_fma_f32 v[192:193], v[94:95], v[202:203], v[192:193] op_sel:[1,0,0]
	s_nop 0
	v_pk_add_f32 v[214:215], v[214:215], v[192:193]
	s_waitcnt lgkmcnt(0)
	v_mov_b32_e32 v193, v196
	v_mov_b32_e32 v196, v189
	v_mov_b32_e32 v192, v188
	v_pk_mul_f32 v[188:189], v[204:205], v[196:197]
	v_mov_b32_e32 v196, v190
	v_pk_fma_f32 v[188:189], v[68:69], v[192:193], v[188:189]
	ds_read_b128 v[192:195], v102 offset:14336
	ds_read_b128 v[200:203], v102 offset:14848
	v_mov_b32_e32 v197, v198
	v_pk_fma_f32 v[188:189], v[206:207], v[196:197], v[188:189]
	v_mov_b32_e32 v198, v191
	v_pk_fma_f32 v[216:217], v[208:209], v[198:199], v[188:189]
	s_waitcnt lgkmcnt(0)
	v_mov_b32_e32 v189, v200
	v_mov_b32_e32 v200, v193
	v_mov_b32_e32 v188, v192
	v_pk_mul_f32 v[190:191], v[212:213], v[200:201]
	v_mov_b32_e32 v196, v194
	v_pk_fma_f32 v[192:193], v[210:211], v[188:189], v[190:191]
	ds_read_b128 v[188:191], v102 offset:16384
	v_mov_b32_e32 v197, v202
	v_pk_fma_f32 v[192:193], v[74:75], v[196:197], v[192:193]
	v_mov_b32_e32 v202, v195
	v_pk_fma_f32 v[218:219], v[76:77], v[202:203], v[192:193]
	ds_read_b128 v[192:195], v102 offset:16896
	s_waitcnt lgkmcnt(1)
	v_mul_f32_e32 v172, v161, v189
	v_fmac_f32_e32 v172, v160, v188
	v_fmac_f32_e32 v172, v162, v190
	v_fmac_f32_e32 v172, v163, v191
	ds_read_b128 v[188:191], v102 offset:17408
	ds_read_b128 v[196:199], v102 offset:17920
	s_waitcnt lgkmcnt(2)
	v_mul_f32_e32 v193, v165, v193
	v_fmac_f32_e32 v193, v164, v192
	v_fmac_f32_e32 v193, v94, v194
	v_add_f32_e32 v172, 0, v172
	v_fmac_f32_e32 v193, v95, v195
	v_add_f32_e32 v172, v172, v193
	s_waitcnt lgkmcnt(0)
	v_mov_b32_e32 v193, v196
	v_mov_b32_e32 v196, v189
	v_mov_b32_e32 v192, v188
	v_pk_mul_f32 v[188:189], v[204:205], v[196:197]
	s_nop 0
	v_pk_fma_f32 v[188:189], v[68:69], v[192:193], v[188:189]
	v_mov_b32_e32 v192, v190
	v_mov_b32_e32 v193, v198
	v_pk_fma_f32 v[196:197], v[206:207], v[192:193], v[188:189]
	v_mov_b32_e32 v198, v191
	ds_read_b128 v[188:191], v102 offset:18432
	ds_read_b128 v[192:195], v102 offset:18944
	v_pk_fma_f32 v[196:197], v[208:209], v[198:199], v[196:197]
	s_nop 0
	v_add_f32_e32 v172, v172, v196
	v_add_f32_e32 v172, v172, v197
	s_waitcnt lgkmcnt(0)
	v_mov_b32_e32 v197, v192
	v_mov_b32_e32 v192, v189
	v_mov_b32_e32 v196, v188
	v_pk_mul_f32 v[188:189], v[212:213], v[192:193]
	v_mov_b32_e32 v192, v190
	v_pk_fma_f32 v[188:189], v[210:211], v[196:197], v[188:189]
	v_mov_b32_e32 v193, v194
	v_pk_fma_f32 v[192:193], v[74:75], v[192:193], v[188:189]
	v_mov_b32_e32 v194, v191
	ds_read_b128 v[188:191], v102 offset:20480
	v_pk_fma_f32 v[192:193], v[76:77], v[194:195], v[192:193]
	s_nop 0
	v_add_f32_e32 v172, v172, v192
	v_add_f32_e32 v220, v172, v193
	ds_read_b128 v[192:195], v102 offset:20992
	s_waitcnt lgkmcnt(1)
	v_mul_f32_e32 v172, v161, v189
	v_fmac_f32_e32 v172, v160, v188
	v_fmac_f32_e32 v172, v162, v190
	v_fmac_f32_e32 v172, v163, v191
	ds_read_b128 v[188:191], v102 offset:21504
	ds_read_b128 v[196:199], v102 offset:22016
	s_waitcnt lgkmcnt(2)
	v_mul_f32_e32 v193, v165, v193
	v_fmac_f32_e32 v193, v164, v192
	v_fmac_f32_e32 v193, v94, v194
	v_add_f32_e32 v172, 0, v172
	v_fmac_f32_e32 v193, v95, v195
	v_add_f32_e32 v172, v172, v193
	s_waitcnt lgkmcnt(0)
; DI unsigned pk2(float a, float b) { fl2_t f = {a, b}; bf2_t r = __builtin_convertvector(f, bf2_t); return __builtin_bit_cast(unsigned, r); }
; #define HSUM(v) do { v += __shfl_xor(v, 16, 64); v += __shfl_xor(v, 8, 64); v += __shfl_xor(v, 4, 64); v += __shfl_xor(v, 2, 64); v += __shfl_xor(v, 1, 64); } while (0)
; DI void phase5(const Params& p, char* lds0) {
;     ...
;         u32x2 o; o[0] = pk2(hv[j * 4 + 0], hv[j * 4 + 1]); o[1] = pk2(hv[j * 4 + 2], hv[j * 4 + 3]);
;         *(u32x2*)(H + (size_t)t * D + c) = o;
;       }
;       float lg[4];
; #pragma unroll
;       for (int n = 0; n < 4; ++n) {
;         float a = 0.f;
; #pragma unroll
;         for (int j = 0; j < 8; ++j) {
;           float4 wv = *(const float4*)(wg + n * 1024 + j * 128 + l32 * 4);
;           a += hv[j * 4 + 0] * wv.x + hv[j * 4 + 1] * wv.y + hv[j * 4 + 2] * wv.z + hv[j * 4 + 3] * wv.w;
;         }
;         HSUM(a);
;         lg[n] = a + p.b_rg[n];
;       }
	v_mov_b32_e32 v193, v196
	v_mov_b32_e32 v196, v189
	v_mov_b32_e32 v192, v188
	v_pk_mul_f32 v[188:189], v[204:205], v[196:197]
	s_nop 0
	v_pk_fma_f32 v[68:69], v[68:69], v[192:193], v[188:189]
	v_mov_b32_e32 v188, v190
	v_mov_b32_e32 v189, v198
	v_pk_fma_f32 v[68:69], v[206:207], v[188:189], v[68:69]
	v_mov_b32_e32 v198, v191
	ds_read_b128 v[188:191], v102 offset:22528
	ds_read_b128 v[192:195], v102 offset:23040
	v_pk_fma_f32 v[68:69], v[208:209], v[198:199], v[68:69]
	ds_read_b128 v[196:199], v102 offset:11264
	ds_read_b128 v[200:203], v102 offset:11776
	v_add_f32_e32 v68, v172, v68
	v_add_f32_e32 v221, v68, v69
	s_waitcnt lgkmcnt(2)
	v_mov_b32_e32 v69, v192
	v_mov_b32_e32 v192, v189
	v_mov_b32_e32 v68, v188
	v_pk_mul_f32 v[188:189], v[212:213], v[192:193]
	s_waitcnt lgkmcnt(1)
	v_mov_b32_e32 v204, v198
	v_pk_fma_f32 v[188:189], v[210:211], v[68:69], v[188:189]
	v_pk_fma_f32 v[68:69], v[154:155], v[170:171], v[30:31]
	s_waitcnt lgkmcnt(0)
	v_mov_b32_e32 v205, v202
	v_cvt_pk_bf16_f32 v172, v68, v69
	global_store_dwordx2 v[166:167], v[172:173], off offset:1792
	v_mov_b32_e32 v166, v196
	v_mov_b32_e32 v167, v200
	v_mov_b32_e32 v200, v197
	v_mov_b32_e32 v202, v199
	ds_read_b128 v[170:173], v102 offset:15360
	ds_read_b128 v[196:199], v102 offset:15872
	v_mov_b32_e32 v212, v71
	v_mov_b32_e32 v213, v69
	v_mov_b32_e32 v210, v70
	v_mov_b32_e32 v211, v68
	v_pk_mul_f32 v[200:201], v[212:213], v[200:201]
	v_mov_b32_e32 v206, v72
	v_mov_b32_e32 v207, v66
	v_pk_fma_f32 v[166:167], v[210:211], v[166:167], v[200:201]
	v_mov_b32_e32 v208, v73
	v_mov_b32_e32 v209, v67
	v_pk_fma_f32 v[166:167], v[206:207], v[204:205], v[166:167]
	v_mov_b32_e32 v192, v190
	v_pk_fma_f32 v[200:201], v[208:209], v[202:203], v[166:167]
	s_waitcnt lgkmcnt(0)
	v_mov_b32_e32 v167, v196
	v_mov_b32_e32 v196, v171
	v_mov_b32_e32 v166, v170
	v_mov_b32_e32 v170, v172
	v_mov_b32_e32 v171, v198
	v_mov_b32_e32 v198, v173
	v_pk_mul_f32 v[172:173], v[212:213], v[196:197]
	v_mov_b32_e32 v196, v84
	v_pk_fma_f32 v[166:167], v[210:211], v[166:167], v[172:173]
	v_mov_b32_e32 v197, v218
	v_pk_fma_f32 v[166:167], v[206:207], v[170:171], v[166:167]
	v_mov_b32_e32 v218, v85
	v_pk_fma_f32 v[170:171], v[208:209], v[198:199], v[166:167]
	v_mov_b32_e32 v166, v168
	v_mov_b32_e32 v167, v216
	v_pk_add_f32 v[166:167], v[214:215], v[166:167]
	v_mov_b32_e32 v216, v169
	v_pk_add_f32 v[172:173], v[166:167], v[216:217]
	global_load_dwordx4 v[166:169], v101, s[28:29]
	v_pk_add_f32 v[172:173], v[172:173], v[196:197]
	v_mov_b32_e32 v193, v194
	v_pk_add_f32 v[84:85], v[172:173], v[218:219]
	v_mov_b32_e32 v172, v200
	v_mov_b32_e32 v173, v170
	v_pk_add_f32 v[84:85], v[84:85], v[172:173]
	v_mov_b32_e32 v170, v201
	v_pk_add_f32 v[84:85], v[84:85], v[170:171]
	ds_bpermute_b32 v170, v176, v84
	ds_bpermute_b32 v171, v176, v85
	v_pk_fma_f32 v[74:75], v[74:75], v[192:193], v[188:189]
	v_mov_b32_e32 v194, v191
	v_pk_fma_f32 v[74:75], v[76:77], v[194:195], v[74:75]
	s_waitcnt lgkmcnt(0)
	v_pk_add_f32 v[84:85], v[84:85], v[170:171]
	v_add_f32_e32 v74, v221, v74
	v_add_f32_e32 v192, v74, v75
	ds_read_b128 v[74:77], v102 offset:19456
	ds_read_b128 v[170:173], v102 offset:19968
	ds_bpermute_b32 v188, v177, v84
	ds_bpermute_b32 v189, v177, v85
	s_waitcnt lgkmcnt(3)
	v_mov_b32_e32 v190, v74
	s_waitcnt lgkmcnt(2)
	v_mov_b32_e32 v191, v170
	v_mov_b32_e32 v170, v75
	v_mov_b32_e32 v74, v76
	v_mov_b32_e32 v75, v172
	v_mov_b32_e32 v172, v77
	v_pk_mul_f32 v[76:77], v[212:213], v[170:171]
	s_waitcnt lgkmcnt(0)
	v_pk_add_f32 v[84:85], v[84:85], v[188:189]
	v_pk_fma_f32 v[76:77], v[210:211], v[190:191], v[76:77]
	ds_bpermute_b32 v188, v178, v84
	v_pk_fma_f32 v[74:75], v[206:207], v[74:75], v[76:77]
	ds_bpermute_b32 v189, v178, v85
	v_pk_fma_f32 v[190:191], v[208:209], v[172:173], v[74:75]
	ds_read_b128 v[74:77], v102 offset:23552
	ds_read_b128 v[170:173], v102 offset:24064
	v_add_f32_e32 v190, v220, v190
	v_add_f32_e32 v193, v190, v191
	ds_bpermute_b32 v194, v176, v193
	s_waitcnt lgkmcnt(2)
	v_mov_b32_e32 v190, v74
	s_waitcnt lgkmcnt(1)
	v_mov_b32_e32 v191, v170
	v_mov_b32_e32 v170, v75
	v_mov_b32_e32 v74, v76
	v_mov_b32_e32 v75, v172
	v_mov_b32_e32 v172, v77
	v_pk_mul_f32 v[76:77], v[212:213], v[170:171]
	s_nop 0
	v_pk_fma_f32 v[76:77], v[210:211], v[190:191], v[76:77]
	s_nop 0
	v_pk_fma_f32 v[74:75], v[206:207], v[74:75], v[76:77]
	s_nop 0
	v_pk_fma_f32 v[74:75], v[208:209], v[172:173], v[74:75]
	s_nop 0
	v_add_f32_e32 v74, v192, v74
	v_add_f32_e32 v76, v74, v75
	ds_bpermute_b32 v77, v176, v76
	v_pk_add_f32 v[74:75], v[84:85], v[188:189]
	s_waitcnt lgkmcnt(1)
	v_add_f32_e32 v84, v193, v194
	ds_bpermute_b32 v85, v177, v84
	s_waitcnt lgkmcnt(1)
	v_add_f32_e32 v170, v76, v77
	ds_bpermute_b32 v171, v177, v170
	ds_bpermute_b32 v76, v179, v74
	s_waitcnt lgkmcnt(2)
	v_add_f32_e32 v84, v84, v85
	ds_bpermute_b32 v85, v178, v84
	ds_bpermute_b32 v77, v179, v75
	s_waitcnt lgkmcnt(3)
	v_add_f32_e32 v170, v170, v171
	ds_bpermute_b32 v171, v178, v170
	s_waitcnt lgkmcnt(2)
	v_add_f32_e32 v84, v84, v85
	ds_bpermute_b32 v85, v179, v84
	s_waitcnt lgkmcnt(2)
	v_pk_add_f32 v[74:75], v[74:75], v[76:77]
	s_waitcnt lgkmcnt(1)
	v_add_f32_e32 v170, v170, v171
	ds_bpermute_b32 v171, v179, v170
	ds_bpermute_b32 v76, v180, v74
	ds_bpermute_b32 v77, v180, v75
	s_waitcnt lgkmcnt(3)
	v_add_f32_e32 v84, v84, v85
	ds_bpermute_b32 v85, v180, v84
	s_waitcnt lgkmcnt(3)
	v_add_f32_e32 v170, v170, v171
	ds_bpermute_b32 v171, v180, v170
	s_waitcnt lgkmcnt(2)
	v_pk_add_f32 v[74:75], v[74:75], v[76:77]
	s_waitcnt lgkmcnt(1)
	v_add_f32_e32 v76, v84, v85
	s_waitcnt vmcnt(0)
	v_pk_add_f32 v[74:75], v[166:167], v[74:75]
	v_add_f32_e32 v168, v168, v76
	s_waitcnt lgkmcnt(0)
; #define HSUM(v) do { v += __shfl_xor(v, 16, 64); v += __shfl_xor(v, 8, 64); v += __shfl_xor(v, 4, 64); v += __shfl_xor(v, 2, 64); v += __shfl_xor(v, 1, 64); } while (0)
; DI void phase5(const Params& p, char* lds0) {
;     ...
;       int g = 0; float gm = lg[0];
; #pragma unroll
;       for (int n = 1; n < 4; ++n) if (lg[n] > gm) { gm = lg[n]; g = n; }
;       float den = 0.f;
; #pragma unroll
;       for (int n = 0; n < 4; ++n) den += __expf(lg[n] - gm);
;       const float pgrp = 1.f / den;
;       float le[8];
; #pragma unroll
;       for (int e = 0; e < 8; ++e) {
;         const float* wr = wg + (4 + g * 8 + e) * 1024;
;         float a = 0.f;
; #pragma unroll
;         for (int j = 0; j < 8; ++j) {
;           float4 wv = *(const float4*)(wr + j * 128 + l32 * 4);
;           a += hv[j * 4 + 0] * wv.x + hv[j * 4 + 1] * wv.y + hv[j * 4 + 2] * wv.z + hv[j * 4 + 3] * wv.w;
;         }
;         HSUM(a);
;         le[e] = a + p.b_re[g * 8 + e];
;       }
	v_add_f32_e32 v76, v170, v171
	v_cmp_gt_f32_e32 vcc, v75, v74
	v_add_f32_e32 v167, v169, v76
	s_nop 0
	v_cndmask_b32_e32 v76, v74, v75, vcc
	v_cmp_gt_f32_e64 s[6:7], v168, v76
	s_nop 1
	v_cndmask_b32_e64 v169, v76, v168, s[6:7]
	v_cndmask_b32_e64 v76, 0, 8, vcc
	v_cndmask_b32_e64 v76, v76, 16, s[6:7]
	v_cmp_gt_f32_e32 vcc, v167, v169
	s_nop 1
	v_cndmask_b32_e64 v166, v76, 24, vcc
	v_lshl_or_b32 v170, v166, 12, v102
	ds_read_b128 v[188:191], v170 offset:26624
	ds_read_b128 v[192:195], v170 offset:27136
	ds_read_b128 v[196:199], v170 offset:24576
	ds_read_b128 v[200:203], v170 offset:28672
	ds_read_b128 v[204:207], v170 offset:27648
	ds_read_b128 v[208:211], v170 offset:28160
	ds_read_b128 v[212:215], v170 offset:25088
	ds_read_b128 v[216:219], v170 offset:29184
	s_waitcnt lgkmcnt(4)
	v_pk_mov_b32 v[76:77], v[196:197], v[200:201] op_sel:[1,0]
	v_mov_b32_e32 v197, v201
	v_pk_mul_f32 v[84:85], v[160:161], v[196:197]
	s_nop 0
	v_pk_fma_f32 v[76:77], v[160:161], v[76:77], v[84:85] op_sel:[1,0,0] op_sel_hi:[0,1,1]
	v_mov_b32_e32 v84, v198
	v_mov_b32_e32 v85, v202
	v_pk_fma_f32 v[76:77], v[162:163], v[84:85], v[76:77] op_sel_hi:[0,1,1]
	v_mov_b32_e32 v202, v199
	v_pk_fma_f32 v[76:77], v[162:163], v[202:203], v[76:77] op_sel:[1,0,0]
	s_waitcnt lgkmcnt(0)
	v_pk_mov_b32 v[84:85], v[212:213], v[216:217] op_sel:[1,0]
	v_mov_b32_e32 v213, v217
	ds_read_b128 v[196:199], v170 offset:26112
	ds_read_b128 v[200:203], v170 offset:25600
	ds_read_b128 v[220:223], v170 offset:29696
	v_pk_mul_f32 v[172:173], v[164:165], v[212:213]
	v_pk_add_f32 v[76:77], v[76:77], 0 op_sel_hi:[1,0]
	v_pk_fma_f32 v[84:85], v[164:165], v[84:85], v[172:173] op_sel:[1,0,0] op_sel_hi:[0,1,1]
	v_mov_b32_e32 v172, v214
	v_mov_b32_e32 v173, v218
	v_pk_fma_f32 v[84:85], v[94:95], v[172:173], v[84:85] op_sel_hi:[0,1,1]
	v_mov_b32_e32 v218, v215
	v_pk_fma_f32 v[84:85], v[94:95], v[218:219], v[84:85] op_sel:[1,0,0]
	ds_read_b128 v[212:215], v170 offset:30208
	v_pk_add_f32 v[76:77], v[76:77], v[84:85]
	s_waitcnt lgkmcnt(1)
	v_pk_mov_b32 v[84:85], v[200:201], v[220:221] op_sel:[1,0]
	v_mov_b32_e32 v201, v221
	v_pk_mul_f32 v[172:173], v[90:91], v[200:201]
	s_nop 0
	v_pk_fma_f32 v[84:85], v[90:91], v[84:85], v[172:173] op_sel:[1,0,0] op_sel_hi:[0,1,1]
	v_mov_b32_e32 v172, v202
	v_mov_b32_e32 v173, v222
	v_pk_fma_f32 v[84:85], v[92:93], v[172:173], v[84:85] op_sel_hi:[0,1,1]
	v_mov_b32_e32 v222, v203
	v_pk_fma_f32 v[84:85], v[92:93], v[222:223], v[84:85] op_sel:[1,0,0]
	ds_read_b128 v[200:203], v170 offset:30720
	v_pk_add_f32 v[76:77], v[76:77], v[84:85]
	s_waitcnt lgkmcnt(1)
	v_pk_mov_b32 v[84:85], v[196:197], v[212:213] op_sel:[1,0]
	v_mov_b32_e32 v197, v213
	v_pk_mul_f32 v[172:173], v[96:97], v[196:197]
	s_nop 0
	v_pk_fma_f32 v[84:85], v[96:97], v[84:85], v[172:173] op_sel:[1,0,0] op_sel_hi:[0,1,1]
	v_mov_b32_e32 v172, v198
	v_mov_b32_e32 v173, v214
	v_pk_fma_f32 v[84:85], v[88:89], v[172:173], v[84:85] op_sel_hi:[0,1,1]
	v_mov_b32_e32 v214, v199
	v_pk_fma_f32 v[84:85], v[88:89], v[214:215], v[84:85] op_sel:[1,0,0]
	ds_read_b128 v[196:199], v170 offset:31232
	v_pk_add_f32 v[76:77], v[76:77], v[84:85]
	s_waitcnt lgkmcnt(1)
	v_pk_mov_b32 v[84:85], v[188:189], v[200:201] op_sel:[1,0]
	v_mov_b32_e32 v189, v201
	v_pk_mul_f32 v[172:173], v[80:81], v[188:189]
	s_nop 0
	v_pk_fma_f32 v[84:85], v[80:81], v[84:85], v[172:173] op_sel:[1,0,0] op_sel_hi:[0,1,1]
	v_mov_b32_e32 v172, v190
	v_mov_b32_e32 v173, v202
	v_pk_fma_f32 v[84:85], v[86:87], v[172:173], v[84:85] op_sel_hi:[0,1,1]
	v_mov_b32_e32 v202, v191
	v_pk_fma_f32 v[84:85], v[86:87], v[202:203], v[84:85] op_sel:[1,0,0]
	ds_read_b128 v[188:191], v170 offset:31744
	v_pk_add_f32 v[76:77], v[76:77], v[84:85]
	v_mov_b32_e32 v84, v193
	s_waitcnt lgkmcnt(1)
	v_mov_b32_e32 v85, v196
	v_pk_mul_f32 v[84:85], v[82:83], v[84:85] op_sel:[1,0] op_sel_hi:[0,1]
	v_mov_b32_e32 v193, v197
	v_pk_fma_f32 v[84:85], v[82:83], v[192:193], v[84:85]
	v_mov_b32_e32 v172, v194
	v_mov_b32_e32 v173, v198
	v_pk_fma_f32 v[84:85], v[78:79], v[172:173], v[84:85] op_sel_hi:[0,1,1]
	v_mov_b32_e32 v198, v195
	v_pk_fma_f32 v[84:85], v[78:79], v[198:199], v[84:85] op_sel:[1,0,0]
	ds_read_b128 v[192:195], v170 offset:32256
	v_pk_add_f32 v[76:77], v[76:77], v[84:85]
	s_waitcnt lgkmcnt(1)
	v_mov_b32_e32 v84, v188
	v_mov_b32_e32 v85, v205
	v_pk_mul_f32 v[84:85], v[70:71], v[84:85]
	v_mov_b32_e32 v205, v189
	v_pk_fma_f32 v[84:85], v[70:71], v[204:205], v[84:85] op_sel:[0,0,1] op_sel_hi:[1,1,0]
	v_mov_b32_e32 v172, v206
	v_mov_b32_e32 v173, v190
	v_pk_fma_f32 v[84:85], v[72:73], v[172:173], v[84:85] op_sel_hi:[0,1,1]
	v_mov_b32_e32 v190, v207
	v_pk_fma_f32 v[84:85], v[72:73], v[190:191], v[84:85] op_sel:[1,0,0]
	ds_read_b128 v[188:191], v170 offset:32768
	v_pk_add_f32 v[76:77], v[76:77], v[84:85]
	s_waitcnt lgkmcnt(1)
	v_pk_mov_b32 v[84:85], v[208:209], v[192:193] op_sel:[1,0]
	v_mov_b32_e32 v209, v193
	v_pk_mul_f32 v[84:85], v[68:69], v[84:85] op_sel:[1,0] op_sel_hi:[0,1]
	v_pk_fma_f32 v[84:85], v[68:69], v[208:209], v[84:85]
	v_mov_b32_e32 v172, v210
	v_mov_b32_e32 v173, v194
	v_pk_fma_f32 v[84:85], v[66:67], v[172:173], v[84:85] op_sel_hi:[0,1,1]
	v_mov_b32_e32 v194, v211
	v_pk_fma_f32 v[84:85], v[66:67], v[194:195], v[84:85] op_sel:[1,0,0]
	ds_read_b128 v[192:195], v170 offset:33280
	s_waitcnt lgkmcnt(1)
	v_mul_f32_e32 v171, v161, v189
	v_fmac_f32_e32 v171, v160, v188
	v_fmac_f32_e32 v171, v162, v190
	v_fmac_f32_e32 v171, v163, v191
	ds_read_b128 v[188:191], v170 offset:33792
	s_waitcnt lgkmcnt(1)
	v_mul_f32_e32 v172, v165, v193
	v_fmac_f32_e32 v172, v164, v192
	v_fmac_f32_e32 v172, v94, v194
	v_add_f32_e32 v171, 0, v171
	v_fmac_f32_e32 v172, v95, v195
	ds_read_b128 v[192:195], v170 offset:34304
	v_add_f32_e32 v171, v171, v172
	s_waitcnt lgkmcnt(1)
; #define HSUM(v) do { v += __shfl_xor(v, 16, 64); v += __shfl_xor(v, 8, 64); v += __shfl_xor(v, 4, 64); v += __shfl_xor(v, 2, 64); v += __shfl_xor(v, 1, 64); } while (0)
; DI void phase5(const Params& p, char* lds0) {
;     ...
;       float le[8];
; #pragma unroll
;       for (int e = 0; e < 8; ++e) {
;         const float* wr = wg + (4 + g * 8 + e) * 1024;
;         float a = 0.f;
; #pragma unroll
;         for (int j = 0; j < 8; ++j) {
;           float4 wv = *(const float4*)(wr + j * 128 + l32 * 4);
;           a += hv[j * 4 + 0] * wv.x + hv[j * 4 + 1] * wv.y + hv[j * 4 + 2] * wv.z + hv[j * 4 + 3] * wv.w;
;         }
;         HSUM(a);
;         le[e] = a + p.b_re[g * 8 + e];
;       }
	v_mul_f32_e32 v172, v91, v189
	v_fmac_f32_e32 v172, v90, v188
	v_fmac_f32_e32 v172, v92, v190
	v_fmac_f32_e32 v172, v93, v191
	ds_read_b128 v[188:191], v170 offset:34816
	v_add_f32_e32 v171, v171, v172
	s_waitcnt lgkmcnt(1)
	v_mul_f32_e32 v172, v97, v193
	v_fmac_f32_e32 v172, v96, v192
	v_fmac_f32_e32 v172, v88, v194
	v_fmac_f32_e32 v172, v89, v195
	ds_read_b128 v[192:195], v170 offset:35328
	v_pk_add_f32 v[76:77], v[76:77], v[84:85]
	v_add_f32_e32 v171, v171, v172
	s_waitcnt lgkmcnt(1)
	v_mul_f32_e32 v172, v81, v189
	ds_bpermute_b32 v84, v176, v76
	ds_bpermute_b32 v85, v176, v77
	v_fmac_f32_e32 v172, v80, v188
	v_fmac_f32_e32 v172, v86, v190
	v_fmac_f32_e32 v172, v87, v191
	ds_read_b128 v[188:191], v170 offset:35840
	v_add_f32_e32 v171, v171, v172
	s_waitcnt lgkmcnt(3)
	v_mul_f32_e32 v172, v83, v193
	v_fmac_f32_e32 v172, v82, v192
	s_waitcnt lgkmcnt(1)
	v_pk_add_f32 v[76:77], v[76:77], v[84:85]
	v_fmac_f32_e32 v172, v78, v194
	ds_bpermute_b32 v84, v177, v76
	ds_bpermute_b32 v85, v177, v77
	v_fmac_f32_e32 v172, v79, v195
	ds_read_b128 v[192:195], v170 offset:36352
	v_add_f32_e32 v171, v171, v172
	s_waitcnt lgkmcnt(3)
	v_mul_f32_e32 v172, v71, v189
	v_fmac_f32_e32 v172, v70, v188
	v_fmac_f32_e32 v172, v72, v190
	v_fmac_f32_e32 v172, v73, v191
	s_waitcnt lgkmcnt(1)
	v_pk_add_f32 v[76:77], v[76:77], v[84:85]
	v_add_f32_e32 v171, v171, v172
	s_waitcnt lgkmcnt(0)
	v_mul_f32_e32 v172, v69, v193
	ds_bpermute_b32 v84, v178, v76
	ds_bpermute_b32 v85, v178, v77
	v_fmac_f32_e32 v172, v68, v192
	v_fmac_f32_e32 v172, v66, v194
	v_fmac_f32_e32 v172, v67, v195
	v_add_f32_e32 v171, v171, v172
	ds_bpermute_b32 v172, v176, v171
	s_waitcnt lgkmcnt(1)
	v_pk_add_f32 v[76:77], v[76:77], v[84:85]
	ds_bpermute_b32 v84, v179, v76
	ds_bpermute_b32 v85, v179, v77
	ds_read_b128 v[188:191], v170 offset:36864
	s_waitcnt lgkmcnt(3)
	v_add_f32_e32 v171, v171, v172
	ds_bpermute_b32 v172, v177, v171
	ds_read_b128 v[192:195], v170 offset:37376
	s_waitcnt lgkmcnt(3)
	v_pk_add_f32 v[76:77], v[76:77], v[84:85]
	s_waitcnt lgkmcnt(2)
	v_mul_f32_e32 v84, v161, v189
	v_fmac_f32_e32 v84, v160, v188
	v_fmac_f32_e32 v84, v162, v190
	v_fmac_f32_e32 v84, v163, v191
	ds_read_b128 v[188:191], v170 offset:37888
	s_waitcnt lgkmcnt(2)
	v_add_f32_e32 v85, v171, v172
	s_waitcnt lgkmcnt(1)
	v_mul_f32_e32 v171, v165, v193
	v_fmac_f32_e32 v171, v164, v192
	v_fmac_f32_e32 v171, v94, v194
	v_add_f32_e32 v84, 0, v84
	v_fmac_f32_e32 v171, v95, v195
	ds_read_b128 v[192:195], v170 offset:38400
	v_add_f32_e32 v84, v84, v171
	s_waitcnt lgkmcnt(1)
	v_mul_f32_e32 v171, v91, v189
	v_fmac_f32_e32 v171, v90, v188
	v_fmac_f32_e32 v171, v92, v190
	v_fmac_f32_e32 v171, v93, v191
	ds_read_b128 v[188:191], v170 offset:38912
	v_add_f32_e32 v84, v84, v171
	s_waitcnt lgkmcnt(1)
	v_mul_f32_e32 v171, v97, v193
	v_fmac_f32_e32 v171, v96, v192
	v_fmac_f32_e32 v171, v88, v194
	v_fmac_f32_e32 v171, v89, v195
	ds_read_b128 v[192:195], v170 offset:39424
	v_add_f32_e32 v84, v84, v171
	s_waitcnt lgkmcnt(1)
	v_mul_f32_e32 v171, v81, v189
	v_fmac_f32_e32 v171, v80, v188
	v_fmac_f32_e32 v171, v86, v190
	v_fmac_f32_e32 v171, v87, v191
	ds_read_b128 v[188:191], v170 offset:39936
	v_add_f32_e32 v84, v84, v171
	s_waitcnt lgkmcnt(1)
	v_mul_f32_e32 v171, v83, v193
	v_fmac_f32_e32 v171, v82, v192
	v_fmac_f32_e32 v171, v78, v194
	v_fmac_f32_e32 v171, v79, v195
	ds_read_b128 v[192:195], v170 offset:40448
	v_add_f32_e32 v84, v84, v171
	s_waitcnt lgkmcnt(1)
	v_mul_f32_e32 v171, v71, v189
	v_fmac_f32_e32 v171, v70, v188
	v_fmac_f32_e32 v171, v72, v190
	v_fmac_f32_e32 v171, v73, v191
	ds_read_b128 v[188:191], v170 offset:40960
	v_add_f32_e32 v84, v84, v171
	s_waitcnt lgkmcnt(1)
	v_mul_f32_e32 v171, v69, v193
	v_fmac_f32_e32 v171, v68, v192
	v_fmac_f32_e32 v171, v66, v194
	v_fmac_f32_e32 v171, v67, v195
	ds_read_b128 v[192:195], v170 offset:41472
	s_waitcnt lgkmcnt(1)
	v_mul_f32_e32 v172, v161, v189
	v_fmac_f32_e32 v172, v160, v188
	v_fmac_f32_e32 v172, v162, v190
	v_fmac_f32_e32 v172, v163, v191
	ds_read_b128 v[188:191], v170 offset:41984
	s_waitcnt lgkmcnt(1)
	v_mul_f32_e32 v173, v165, v193
	v_fmac_f32_e32 v173, v164, v192
	v_fmac_f32_e32 v173, v94, v194
	v_add_f32_e32 v172, 0, v172
	v_fmac_f32_e32 v173, v95, v195
	ds_read_b128 v[192:195], v170 offset:42496
	v_add_f32_e32 v172, v172, v173
	s_waitcnt lgkmcnt(1)
	v_mul_f32_e32 v173, v91, v189
	v_fmac_f32_e32 v173, v90, v188
	v_fmac_f32_e32 v173, v92, v190
	v_fmac_f32_e32 v173, v93, v191
	ds_read_b128 v[188:191], v170 offset:43008
	v_add_f32_e32 v172, v172, v173
	s_waitcnt lgkmcnt(1)
	v_mul_f32_e32 v173, v97, v193
	v_fmac_f32_e32 v173, v96, v192
	v_fmac_f32_e32 v173, v88, v194
	v_fmac_f32_e32 v173, v89, v195
	ds_read_b128 v[192:195], v170 offset:43520
	v_add_f32_e32 v172, v172, v173
	s_waitcnt lgkmcnt(1)
	v_mul_f32_e32 v173, v81, v189
	v_fmac_f32_e32 v173, v80, v188
	v_fmac_f32_e32 v173, v86, v190
	v_fmac_f32_e32 v173, v87, v191
	ds_read_b128 v[188:191], v170 offset:44032
	v_add_f32_e32 v172, v172, v173
	s_waitcnt lgkmcnt(1)
	v_mul_f32_e32 v173, v83, v193
	v_fmac_f32_e32 v173, v82, v192
	v_fmac_f32_e32 v173, v78, v194
	v_fmac_f32_e32 v173, v79, v195
	ds_read_b128 v[192:195], v170 offset:44544
	v_add_f32_e32 v172, v172, v173
	s_waitcnt lgkmcnt(1)
	v_mul_f32_e32 v173, v71, v189
	v_fmac_f32_e32 v173, v70, v188
	v_fmac_f32_e32 v173, v72, v190
	v_fmac_f32_e32 v173, v73, v191
	v_add_f32_e32 v172, v172, v173
	s_waitcnt lgkmcnt(0)
	v_mul_f32_e32 v173, v69, v193
	v_fmac_f32_e32 v173, v68, v192
	v_fmac_f32_e32 v173, v66, v194
	v_fmac_f32_e32 v173, v67, v195
	v_add_f32_e32 v84, v84, v171
	v_add_f32_e32 v172, v172, v173
	ds_bpermute_b32 v171, v176, v84
	ds_bpermute_b32 v173, v176, v172
	ds_bpermute_b32 v188, v178, v85
	ds_read_b128 v[192:195], v170 offset:45056
	s_waitcnt lgkmcnt(3)
; #define HSUM(v) do { v += __shfl_xor(v, 16, 64); v += __shfl_xor(v, 8, 64); v += __shfl_xor(v, 4, 64); v += __shfl_xor(v, 2, 64); v += __shfl_xor(v, 1, 64); } while (0)
; DI void phase5(const Params& p, char* lds0) {
;     ...
;       float le[8];
; #pragma unroll
;       for (int e = 0; e < 8; ++e) {
;         const float* wr = wg + (4 + g * 8 + e) * 1024;
;         float a = 0.f;
; #pragma unroll
;         for (int j = 0; j < 8; ++j) {
;           float4 wv = *(const float4*)(wr + j * 128 + l32 * 4);
;           a += hv[j * 4 + 0] * wv.x + hv[j * 4 + 1] * wv.y + hv[j * 4 + 2] * wv.z + hv[j * 4 + 3] * wv.w;
;         }
;         HSUM(a);
;         le[e] = a + p.b_re[g * 8 + e];
;       }
	v_add_f32_e32 v171, v84, v171
	s_waitcnt lgkmcnt(2)
	v_add_f32_e32 v172, v172, v173
	ds_bpermute_b32 v189, v177, v171
	ds_bpermute_b32 v173, v177, v172
	s_waitcnt lgkmcnt(3)
	v_add_f32_e32 v188, v85, v188
	ds_bpermute_b32 v190, v179, v188
	ds_bpermute_b32 v84, v180, v76
	s_waitcnt lgkmcnt(3)
	v_add_f32_e32 v171, v171, v189
	s_waitcnt lgkmcnt(2)
	v_add_f32_e32 v172, v172, v173
	ds_bpermute_b32 v189, v178, v171
	ds_bpermute_b32 v173, v178, v172
	ds_bpermute_b32 v85, v180, v77
	s_waitcnt lgkmcnt(2)
	v_add_f32_e32 v189, v171, v189
	v_add_f32_e32 v171, v188, v190
	s_waitcnt lgkmcnt(1)
	v_add_f32_e32 v190, v172, v173
	ds_bpermute_b32 v191, v179, v189
	ds_bpermute_b32 v196, v179, v190
	ds_bpermute_b32 v172, v180, v171
	s_waitcnt lgkmcnt(2)
	v_add_f32_e32 v173, v189, v191
	s_waitcnt lgkmcnt(1)
	v_add_f32_e32 v189, v190, v196
	ds_read_b128 v[196:199], v170 offset:45568
	v_mul_f32_e32 v191, v161, v193
	v_fmac_f32_e32 v191, v160, v192
	v_fmac_f32_e32 v191, v162, v194
	v_fmac_f32_e32 v191, v163, v195
	s_waitcnt lgkmcnt(0)
	v_mul_f32_e32 v197, v165, v197
	v_fmac_f32_e32 v197, v164, v196
	ds_read_b128 v[192:195], v170 offset:46080
	v_fmac_f32_e32 v197, v94, v198
	v_add_f32_e32 v191, 0, v191
	v_fmac_f32_e32 v197, v95, v199
	v_add_f32_e32 v191, v191, v197
	ds_read_b128 v[196:199], v170 offset:46592
	s_waitcnt lgkmcnt(1)
	v_mul_f32_e32 v193, v91, v193
	v_fmac_f32_e32 v193, v90, v192
	v_fmac_f32_e32 v193, v92, v194
	v_fmac_f32_e32 v193, v93, v195
	s_waitcnt lgkmcnt(0)
	v_mul_f32_e32 v197, v97, v197
	v_add_f32_e32 v191, v191, v193
	v_fmac_f32_e32 v197, v96, v196
	ds_read_b128 v[192:195], v170 offset:47104
	v_fmac_f32_e32 v197, v88, v198
	v_fmac_f32_e32 v197, v89, v199
	v_add_f32_e32 v191, v191, v197
	ds_read_b128 v[196:199], v170 offset:47616
	s_waitcnt lgkmcnt(1)
	v_mul_f32_e32 v193, v81, v193
	v_fmac_f32_e32 v193, v80, v192
	v_fmac_f32_e32 v193, v86, v194
	v_fmac_f32_e32 v193, v87, v195
	s_waitcnt lgkmcnt(0)
	v_mul_f32_e32 v197, v83, v197
	v_add_f32_e32 v191, v191, v193
	v_fmac_f32_e32 v197, v82, v196
	ds_read_b128 v[192:195], v170 offset:48128
	v_fmac_f32_e32 v197, v78, v198
	v_fmac_f32_e32 v197, v79, v199
	v_add_f32_e32 v191, v191, v197
	ds_read_b128 v[196:199], v170 offset:48640
	s_waitcnt lgkmcnt(1)
	v_mul_f32_e32 v193, v71, v193
	v_fmac_f32_e32 v193, v70, v192
	v_fmac_f32_e32 v193, v72, v194
	v_fmac_f32_e32 v193, v73, v195
	s_waitcnt lgkmcnt(0)
	v_mul_f32_e32 v197, v69, v197
	v_add_f32_e32 v191, v191, v193
	v_fmac_f32_e32 v197, v68, v196
	ds_read_b128 v[192:195], v170 offset:49152
	v_fmac_f32_e32 v197, v66, v198
	v_fmac_f32_e32 v197, v67, v199
	v_add_f32_e32 v191, v191, v197
	ds_read_b128 v[196:199], v170 offset:49664
	s_waitcnt lgkmcnt(1)
	v_mul_f32_e32 v193, v161, v193
	v_fmac_f32_e32 v193, v160, v192
	v_fmac_f32_e32 v193, v162, v194
	v_fmac_f32_e32 v193, v163, v195
	s_waitcnt lgkmcnt(0)
	v_mul_f32_e32 v197, v165, v197
	v_add_f32_e32 v201, 0, v193
	v_fmac_f32_e32 v197, v164, v196
	ds_read_b128 v[192:195], v170 offset:50176
	v_fmac_f32_e32 v197, v94, v198
	v_fmac_f32_e32 v197, v95, v199
	v_add_f32_e32 v201, v201, v197
	ds_read_b128 v[196:199], v170 offset:50688
	s_waitcnt lgkmcnt(1)
	v_mul_f32_e32 v193, v91, v193
	v_fmac_f32_e32 v193, v90, v192
	v_fmac_f32_e32 v193, v92, v194
	v_fmac_f32_e32 v193, v93, v195
	s_waitcnt lgkmcnt(0)
	v_mul_f32_e32 v197, v97, v197
	v_add_f32_e32 v201, v201, v193
	v_fmac_f32_e32 v197, v96, v196
	ds_read_b128 v[192:195], v170 offset:51200
	v_fmac_f32_e32 v197, v88, v198
	v_fmac_f32_e32 v197, v89, v199
	v_add_f32_e32 v201, v201, v197
	ds_read_b128 v[196:199], v170 offset:51712
	s_waitcnt lgkmcnt(1)
	v_mul_f32_e32 v193, v81, v193
	v_fmac_f32_e32 v193, v80, v192
	v_fmac_f32_e32 v193, v86, v194
	v_fmac_f32_e32 v193, v87, v195
	s_waitcnt lgkmcnt(0)
	v_mul_f32_e32 v197, v83, v197
	v_add_f32_e32 v201, v201, v193
	v_fmac_f32_e32 v197, v82, v196
	ds_read_b128 v[192:195], v170 offset:52224
	v_fmac_f32_e32 v197, v78, v198
	v_fmac_f32_e32 v197, v79, v199
	v_add_f32_e32 v201, v201, v197
	ds_read_b128 v[196:199], v170 offset:52736
	s_waitcnt lgkmcnt(1)
	v_mul_f32_e32 v193, v71, v193
	v_fmac_f32_e32 v193, v70, v192
	v_fmac_f32_e32 v193, v72, v194
	v_fmac_f32_e32 v193, v73, v195
	s_waitcnt lgkmcnt(0)
	v_mul_f32_e32 v197, v69, v197
	v_add_f32_e32 v201, v201, v193
	v_fmac_f32_e32 v197, v68, v196
	ds_read_b128 v[192:195], v170 offset:53248
	v_fmac_f32_e32 v197, v66, v198
	v_fmac_f32_e32 v197, v67, v199
	v_add_f32_e32 v201, v201, v197
	ds_read_b128 v[196:199], v170 offset:53760
	s_waitcnt lgkmcnt(1)
	v_mul_f32_e32 v161, v161, v193
	v_fmac_f32_e32 v161, v160, v192
	v_fmac_f32_e32 v161, v162, v194
	v_fmac_f32_e32 v161, v163, v195
	s_waitcnt lgkmcnt(0)
	v_mul_f32_e32 v165, v165, v197
	v_add_f32_e32 v192, 0, v161
	v_fmac_f32_e32 v165, v164, v196
	ds_read_b128 v[160:163], v170 offset:54272
	v_fmac_f32_e32 v165, v94, v198
	v_fmac_f32_e32 v165, v95, v199
	v_add_f32_e32 v94, v192, v165
	ds_read_b128 v[192:195], v170 offset:54784
	s_waitcnt lgkmcnt(1)
	v_mul_f32_e32 v91, v91, v161
	v_fmac_f32_e32 v91, v90, v160
	v_fmac_f32_e32 v91, v92, v162
	v_fmac_f32_e32 v91, v93, v163
	s_waitcnt lgkmcnt(0)
	v_mul_f32_e32 v95, v97, v193
	v_add_f32_e32 v94, v94, v91
	v_fmac_f32_e32 v95, v96, v192
	ds_read_b128 v[90:93], v170 offset:55296
	v_fmac_f32_e32 v95, v88, v194
	v_fmac_f32_e32 v95, v89, v195
	v_add_f32_e32 v88, v94, v95
	ds_read_b128 v[94:97], v170 offset:55808
	s_waitcnt lgkmcnt(1)
	v_mul_f32_e32 v81, v81, v91
	v_fmac_f32_e32 v81, v80, v90
	v_fmac_f32_e32 v81, v86, v92
	v_fmac_f32_e32 v81, v87, v93
	s_waitcnt lgkmcnt(0)
; DI void phase5(const Params& p, char* lds0) {
;     ...
;       int i1 = 0; float v1 = le[0];
; #pragma unroll
;       for (int e = 1; e < 8; ++e) if (le[e] > v1) { v1 = le[e]; i1 = e; }
;       int i2 = -1; float v2 = -3.0e38f;
; #pragma unroll
;       for (int e = 0; e < 8; ++e) if (e != i1 && le[e] > v2) { v2 = le[e]; i2 = e; }
;       const float e2 = __expf(v2 - v1);
;       const float w1 = pgrp / (1.f + e2), w2 = pgrp * e2 / (1.f + e2);
;       if (l32 == 0) {
;         const int li0 = (g * 8 + i1) * 2, li1 = (g * 8 + i2) * 2 + 1;
;         const int lp0 = atomicAdd(&hist[li0], 1), lp1 = atomicAdd(&hist[li1], 1);
;         info[tl * 4 + 0] = li0; info[tl * 4 + 1] = li1; info[tl * 4 + 2] = lp0; info[tl * 4 + 3] = lp1;
;         gate[t] = w1; gate[T + t] = w2;
;       }
	v_mul_f32_e32 v87, v83, v95
	v_fmac_f32_e32 v87, v82, v94
	v_fmac_f32_e32 v87, v78, v96
	v_add_f32_e32 v86, v88, v81
	ds_read_b128 v[80:83], v170 offset:56320
	v_fmac_f32_e32 v87, v79, v97
	v_add_f32_e32 v78, v86, v87
	ds_read_b128 v[86:89], v170 offset:56832
	ds_bpermute_b32 v200, v176, v191
	s_waitcnt lgkmcnt(2)
	v_mul_f32_e32 v71, v71, v81
	v_fmac_f32_e32 v71, v70, v80
	v_fmac_f32_e32 v71, v72, v82
	s_waitcnt lgkmcnt(1)
	v_mul_f32_e32 v69, v69, v87
	v_fmac_f32_e32 v69, v68, v86
	v_fmac_f32_e32 v71, v73, v83
	v_fmac_f32_e32 v69, v66, v88
	v_add_f32_e32 v70, v78, v71
	v_fmac_f32_e32 v69, v67, v89
	v_add_f32_e32 v66, v70, v69
	ds_bpermute_b32 v202, v176, v201
	ds_bpermute_b32 v67, v176, v66
	s_waitcnt lgkmcnt(2)
	v_add_f32_e32 v68, v191, v200
	ds_bpermute_b32 v69, v177, v68
	ds_bpermute_b32 v188, v180, v173
	s_waitcnt lgkmcnt(3)
	v_add_f32_e32 v70, v201, v202
	s_waitcnt lgkmcnt(2)
	v_add_f32_e32 v66, v66, v67
	ds_bpermute_b32 v71, v177, v70
	ds_bpermute_b32 v67, v177, v66
	s_waitcnt lgkmcnt(3)
	v_add_f32_e32 v68, v68, v69
	ds_bpermute_b32 v69, v178, v68
	ds_bpermute_b32 v190, v180, v189
	s_waitcnt lgkmcnt(3)
	v_add_f32_e32 v70, v70, v71
	s_waitcnt lgkmcnt(2)
	v_add_f32_e32 v66, v66, v67
	ds_bpermute_b32 v71, v178, v70
	ds_bpermute_b32 v67, v178, v66
	s_waitcnt lgkmcnt(3)
	v_add_f32_e32 v68, v68, v69
	ds_bpermute_b32 v69, v179, v68
	s_waitcnt lgkmcnt(2)
	v_add_f32_e32 v70, v70, v71
	s_waitcnt lgkmcnt(1)
	v_add_f32_e32 v72, v66, v67
	ds_bpermute_b32 v71, v179, v70
	ds_bpermute_b32 v73, v179, v72
	s_waitcnt lgkmcnt(2)
	v_add_f32_e32 v66, v68, v69
	ds_bpermute_b32 v67, v180, v66
	s_waitcnt lgkmcnt(2)
	v_add_f32_e32 v68, v70, v71
	s_waitcnt lgkmcnt(1)
	v_add_f32_e32 v70, v72, v73
	ds_bpermute_b32 v69, v180, v68
	ds_bpermute_b32 v71, v180, v70
	s_and_saveexec_b64 s[38:39], s[4:5]
	s_cbranch_execz .LBB0_255
	v_lshlrev_b32_e32 v72, 2, v166
	global_load_dwordx4 v[78:81], v72, s[30:31] offset:16
	global_load_dwordx4 v[86:89], v72, s[30:31]
	s_waitcnt lgkmcnt(1)
	v_add_f32_e32 v68, v68, v69
	v_add_f32_e32 v69, v66, v67
	v_cndmask_b32_e32 v66, v169, v167, vcc
	v_sub_f32_e32 v67, v74, v66
	v_sub_f32_e32 v74, v75, v66
	v_mul_f32_e32 v67, 0x3fb8aa3b, v67
	v_sub_f32_e32 v75, v168, v66
	v_mul_f32_e32 v74, 0x3fb8aa3b, v74
	v_exp_f32_e32 v67, v67
	v_sub_f32_e32 v66, v167, v66
	v_mul_f32_e32 v75, 0x3fb8aa3b, v75
	v_exp_f32_e32 v74, v74
	v_mul_f32_e32 v66, 0x3fb8aa3b, v66
	v_exp_f32_e32 v75, v75
	v_exp_f32_e32 v66, v66
	v_add_f32_e32 v67, 0, v67
	v_add_f32_e32 v67, v74, v67
	v_add_f32_e32 v67, v75, v67
	v_add_f32_e32 v74, v66, v67
	v_div_scale_f32 v75, s[6:7], v74, v74, 1.0
	v_rcp_f32_e32 v82, v75
	v_pk_add_f32 v[66:67], v[76:77], v[84:85]
	v_div_scale_f32 v76, vcc, 1.0, v74, 1.0
	v_fma_f32 v77, -v75, v82, 1.0
	v_fmac_f32_e32 v82, v77, v82
	v_mul_f32_e32 v77, v76, v82
	v_fma_f32 v83, -v75, v77, v76
	v_fmac_f32_e32 v77, v83, v82
	v_fma_f32 v75, -v75, v77, v76
	v_add_f32_e32 v73, v171, v172
	v_div_fmas_f32 v75, v75, v82, v77
	v_div_fixup_f32 v74, v75, v74, 1.0
	v_add_f32_e32 v72, v173, v188
	s_waitcnt lgkmcnt(0)
	v_add_f32_e32 v70, v70, v71
	v_add_f32_e32 v71, v189, v190
	s_waitcnt vmcnt(1)
	v_add_f32_e32 v71, v71, v78
	s_waitcnt vmcnt(0)
	v_pk_add_f32 v[66:67], v[66:67], v[86:87]
	v_add_f32_e32 v73, v73, v88
	v_cmp_gt_f32_e32 vcc, v67, v66
	v_add_f32_e32 v72, v72, v89
	v_add_f32_e32 v69, v69, v79
	v_cndmask_b32_e32 v75, v66, v67, vcc
	v_cmp_gt_f32_e64 s[8:9], v73, v75
	v_cndmask_b32_e64 v76, 0, 1, vcc
	v_add_f32_e32 v68, v68, v80
	v_cndmask_b32_e64 v75, v75, v73, s[8:9]
	v_cmp_gt_f32_e32 vcc, v72, v75
	v_cndmask_b32_e64 v76, v76, 2, s[8:9]
	v_add_f32_e32 v70, v70, v81
	v_cndmask_b32_e32 v75, v75, v72, vcc
	v_cmp_gt_f32_e64 s[8:9], v71, v75
	v_cndmask_b32_e64 v76, v76, 3, vcc
	v_cmp_nlt_f32_e64 s[6:7], s41, v66
	v_cndmask_b32_e64 v75, v75, v71, s[8:9]
	v_cmp_gt_f32_e32 vcc, v69, v75
	v_cndmask_b32_e64 v76, v76, 4, s[8:9]
	s_nop 0
	v_cndmask_b32_e32 v75, v75, v69, vcc
	v_cmp_gt_f32_e64 s[8:9], v68, v75
	v_cndmask_b32_e64 v76, v76, 5, vcc
	s_nop 0
	v_cndmask_b32_e64 v75, v75, v68, s[8:9]
	v_cndmask_b32_e64 v76, v76, 6, s[8:9]
	v_cmp_ngt_f32_e32 vcc, v70, v75
	s_and_b64 s[46:47], s[8:9], vcc
	s_nop 0
	v_cndmask_b32_e32 v76, 7, v76, vcc
	v_cmp_eq_u32_e64 s[18:19], 0, v76
	s_or_b64 s[6:7], s[18:19], s[6:7]
	v_cndmask_b32_e64 v66, v66, v185, s[6:7]
	v_cmp_ne_u32_e64 s[16:17], 1, v76
	v_cmp_gt_f32_e64 s[18:19], v67, v66
	v_cndmask_b32_e64 v77, 0, -1, s[6:7]
	s_and_b64 s[6:7], s[16:17], s[18:19]
	v_cndmask_b32_e64 v66, v66, v67, s[6:7]
	v_cmp_ne_u32_e64 s[14:15], 2, v76
	v_cmp_gt_f32_e64 s[16:17], v73, v66
	v_cndmask_b32_e64 v67, v77, 1, s[6:7]
	s_and_b64 s[6:7], s[14:15], s[16:17]
	v_cndmask_b32_e64 v66, v66, v73, s[6:7]
	v_cmp_ne_u32_e64 s[12:13], 3, v76
	v_cmp_gt_f32_e64 s[14:15], v72, v66
	v_cndmask_b32_e64 v67, v67, 2, s[6:7]
	s_and_b64 s[6:7], s[12:13], s[14:15]
	v_cndmask_b32_e64 v66, v66, v72, s[6:7]
	v_cmp_ne_u32_e64 s[10:11], 4, v76
	v_cmp_gt_f32_e64 s[12:13], v71, v66
	v_cndmask_b32_e64 v67, v67, 3, s[6:7]
	s_and_b64 s[6:7], s[10:11], s[12:13]
	v_cndmask_b32_e64 v66, v66, v71, s[6:7]
	v_cmp_ne_u32_e64 s[8:9], 5, v76
	v_cmp_gt_f32_e64 s[10:11], v69, v66
	s_and_b64 s[8:9], s[8:9], s[10:11]
	v_cndmask_b32_e64 v66, v66, v69, s[8:9]
	v_cmp_ngt_f32_e64 s[10:11], v68, v66
	s_or_b64 s[10:11], s[46:47], s[10:11]
	v_cndmask_b32_e32 v75, v70, v75, vcc
	v_cndmask_b32_e64 v66, v68, v66, s[10:11]
	v_cmp_gt_f32_e64 s[12:13], v70, v66
	s_and_b64 vcc, vcc, s[12:13]
	v_cndmask_b32_e32 v66, v66, v70, vcc
	v_sub_f32_e32 v66, v66, v75
	v_mul_f32_e32 v66, 0x3fb8aa3b, v66
	v_exp_f32_e32 v66, v66
	v_cndmask_b32_e64 v67, v67, 4, s[6:7]
	v_cndmask_b32_e64 v67, v67, 5, s[8:9]
	v_cndmask_b32_e64 v67, 6, v67, s[10:11]
	v_mul_f32_e32 v68, v74, v66
	v_add_f32_e32 v66, 1.0, v66
	v_cndmask_b32_e64 v67, v67, 7, vcc
	v_rcp_f32_e32 v69, v66
	s_nop 0
	v_mul_f32_e32 v70, v68, v69
	v_or_b32_e32 v75, v76, v166
	v_add_u32_e32 v67, v67, v166
	v_lshl_add_u32 v68, v75, 3, v1
	ds_add_rtn_u32 v68, v68, v183
	v_lshl_add_u32 v69, v67, 3, v1
	ds_add_rtn_u32 v69, v69, v183 offset:4
	v_rcp_f32_e32 v71, v66
	s_nop 0
	v_mul_f32_e32 v71, v74, v71
	v_lshlrev_b32_e32 v66, 1, v75
	v_lshl_or_b32 v67, v67, 1, 1
	s_waitcnt lgkmcnt(0)
	ds_write_b128 v187, v[66:69]
	v_lshl_add_u64 v[66:67], v[158:159], 2, s[22:23]
	global_store_dword v[66:67], v71, off
	v_add_co_u32_e32 v66, vcc, 0x60000, v66
	s_nop 1
	v_addc_co_u32_e32 v67, vcc, 0, v67, vcc
	global_store_dword v[66:67], v70, off
	s_branch .LBB0_255
